# G4 epilogue ss loads hoisted (counted waits) + E1 row pass: hoist loop-invariant wconv/gkv loads, real next-row prefetch (counted vmcnt at loop bottom)
# speedup vs baseline: 1.0126x; 1.0126x over previous
; __device__ __forceinline__ unsigned pkbf(float lo, float hi) { f2_t v = {lo, hi}; return __builtin_bit_cast(unsigned, __builtin_convertvector(v, bf2_t)); }
; __device__ __forceinline__ float fsigmoid(float g) { return __builtin_amdgcn_rcpf(1.0f + __builtin_amdgcn_exp2f(-1.44269504f * g)); }
;     __device__ __forceinline__ void operator()(const f32x4 (&acc)[2][2][4][2], const Unit& u, int wr, int wc, int fr, int fq) const {
;         const int row0 = u.pm * BM + wr * 64 + fr, col0 = u.pn * HALF + wc * 32 + 8 * fq;
; #pragma unroll
;         for (int ai = 0; ai < 2; ++ai)
; #pragma unroll
;             for (int m = 0; m < 4; ++m) { const int row = row0 + ai * HALF + m * 16; const float sc = rsqrtf(ss[row] * invk + eps);
;                 float h[8];
; #pragma unroll
;                 for (int n = 0; n < 2; ++n)
; #pragma unroll
;                     for (int j = 0; j < 4; ++j) { const float g = acc[ai][0][m][n][j] * sc, up = acc[ai][1][m][n][j] * sc; h[4 * n + j] = g * fsigmoid(g) * up; }
;                 u32x4 w; w.x = pkbf(h[0], h[1]); w.y = pkbf(h[2], h[3]); w.z = pkbf(h[4], h[5]); w.w = pkbf(h[6], h[7]);
;                 *(u32x4*)(O + (size_t)row * ldc + col0) = w; }
.LBB0_47:
	v_lshl_add_u32 v146, s58, 8, v152
	v_ashrrev_i32_e32 v147, 31, v146
	v_lshl_add_u64 v[148:149], v[146:147], 2, s[8:9]
	global_load_dword v192, v[148:149], off
	global_load_dword v193, v[148:149], off offset:64
	global_load_dword v194, v[148:149], off offset:128
	global_load_dword v195, v[148:149], off offset:192
	global_load_dword v196, v[148:149], off offset:512
	global_load_dword v197, v[148:149], off offset:576
	global_load_dword v198, v[148:149], off offset:640
	global_load_dword v199, v[148:149], off offset:704
	v_lshl_or_b32 v150, s0, 7, v154
	v_ashrrev_i32_e32 v151, 31, v150
	s_mov_b64 s[58:59], -1
	s_waitcnt vmcnt(7)
	v_fmamk_f32 v147, v192, 0x3a800000, v134
	v_cmp_gt_f32_e32 vcc, s13, v147
	v_mul_f32_e32 v156, 0x4b800000, v147
	s_nop 0
	v_cndmask_b32_e32 v147, v147, v156, vcc
	v_rsq_f32_e32 v147, v147
	s_nop 0
	v_mul_f32_e32 v156, 0x45800000, v147
	v_cndmask_b32_e32 v156, v147, v156, vcc
	v_pk_mul_f32 v[124:125], v[124:125], v[156:157] op_sel_hi:[1,0]
	v_pk_mul_f32 v[116:117], v[116:117], v[156:157] op_sel_hi:[1,0]
	v_mul_f32_e32 v147, 0xbfb8aa3b, v124
	v_exp_f32_e32 v147, v147
	v_pk_mul_f32 v[118:119], v[118:119], v[156:157] op_sel_hi:[1,0]
	v_pk_mul_f32 v[120:121], v[120:121], v[156:157] op_sel_hi:[1,0]
	v_pk_mul_f32 v[112:113], v[112:113], v[156:157] op_sel_hi:[1,0]
	v_add_f32_e32 v147, 1.0, v147
	v_rcp_f32_e32 v158, v147
	v_mul_f32_e32 v147, 0xbfb8aa3b, v125
	v_exp_f32_e32 v147, v147
	v_pk_mul_f32 v[114:115], v[114:115], v[156:157] op_sel_hi:[1,0]
	v_add_f32_e32 v147, 1.0, v147
	v_rcp_f32_e32 v159, v147
	s_nop 0
	v_pk_mul_f32 v[124:125], v[124:125], v[158:159]
	s_nop 0
	v_pk_mul_f32 v[116:117], v[116:117], v[124:125]
	v_pk_mul_f32 v[124:125], v[126:127], v[156:157] op_sel_hi:[1,0]
	s_nop 0
	v_mul_f32_e32 v126, 0xbfb8aa3b, v124
	v_mul_f32_e32 v127, 0xbfb8aa3b, v125
	v_exp_f32_e32 v126, v126
	v_exp_f32_e32 v127, v127
	v_add_f32_e32 v126, 1.0, v126
	v_add_f32_e32 v127, 1.0, v127
	v_rcp_f32_e32 v126, v126
	v_rcp_f32_e32 v127, v127
	s_nop 0
	v_pk_mul_f32 v[124:125], v[124:125], v[126:127]
	s_nop 0
	v_pk_mul_f32 v[118:119], v[118:119], v[124:125]
	v_mul_f32_e32 v124, 0xbfb8aa3b, v120
	v_mul_f32_e32 v125, 0xbfb8aa3b, v121
	v_exp_f32_e32 v124, v124
	v_exp_f32_e32 v125, v125
	v_add_f32_e32 v124, 1.0, v124
	v_add_f32_e32 v125, 1.0, v125
	v_rcp_f32_e32 v124, v124
	v_rcp_f32_e32 v125, v125
	s_nop 0
	v_pk_mul_f32 v[120:121], v[120:121], v[124:125]
	s_nop 0
	v_pk_mul_f32 v[120:121], v[112:113], v[120:121]
	v_pk_mul_f32 v[112:113], v[122:123], v[156:157] op_sel_hi:[1,0]
	s_nop 0
	v_mul_f32_e32 v122, 0xbfb8aa3b, v112
	v_mul_f32_e32 v123, 0xbfb8aa3b, v113
	v_exp_f32_e32 v122, v122
	v_exp_f32_e32 v123, v123
	v_add_f32_e32 v122, 1.0, v122
	v_add_f32_e32 v123, 1.0, v123
	v_rcp_f32_e32 v122, v122
	v_rcp_f32_e32 v123, v123
	s_nop 0
	v_pk_mul_f32 v[112:113], v[112:113], v[122:123]
	s_nop 0
	v_pk_mul_f32 v[122:123], v[114:115], v[112:113]
	v_cvt_pk_bf16_f32 v112, v116, v117
	v_mov_b64_e32 v[116:117], s[34:35]
	v_cvt_pk_bf16_f32 v113, v118, v119
	v_cvt_pk_bf16_f32 v114, v120, v121
	v_mad_i64_i32 v[120:121], s[0:1], v146, s73, v[116:117]
	v_lshlrev_b64 v[118:119], 1, v[150:151]
	v_cvt_pk_bf16_f32 v115, v122, v123
	v_lshl_add_u64 v[120:121], v[120:121], 0, v[118:119]
	global_store_dwordx4 v[120:121], v[112:115], off
	s_nop 1
	v_or_b32_e32 v112, 16, v146
	s_waitcnt vmcnt(7)
	v_fmamk_f32 v113, v193, 0x3a800000, v134
	v_cmp_gt_f32_e32 vcc, s13, v113
	v_mul_f32_e32 v114, 0x4b800000, v113
	s_nop 0
	v_cndmask_b32_e32 v113, v113, v114, vcc
	v_rsq_f32_e32 v113, v113
	s_nop 0
	v_mul_f32_e32 v114, 0x45800000, v113
	v_cndmask_b32_e32 v114, v113, v114, vcc
	v_pk_mul_f32 v[108:109], v[108:109], v[114:115] op_sel_hi:[1,0]
	v_pk_mul_f32 v[100:101], v[100:101], v[114:115] op_sel_hi:[1,0]
	v_mul_f32_e32 v113, 0xbfb8aa3b, v108
	v_exp_f32_e32 v113, v113
	v_pk_mul_f32 v[102:103], v[102:103], v[114:115] op_sel_hi:[1,0]
	v_pk_mul_f32 v[104:105], v[104:105], v[114:115] op_sel_hi:[1,0]
	v_pk_mul_f32 v[96:97], v[96:97], v[114:115] op_sel_hi:[1,0]
	v_add_f32_e32 v113, 1.0, v113
	v_rcp_f32_e32 v120, v113
	v_mul_f32_e32 v113, 0xbfb8aa3b, v109
	v_exp_f32_e32 v113, v113
	v_pk_mul_f32 v[98:99], v[98:99], v[114:115] op_sel_hi:[1,0]
	v_add_f32_e32 v113, 1.0, v113
	v_rcp_f32_e32 v121, v113
	s_nop 0
	v_pk_mul_f32 v[108:109], v[108:109], v[120:121]
	s_nop 0
	v_pk_mul_f32 v[100:101], v[100:101], v[108:109]
	v_pk_mul_f32 v[108:109], v[110:111], v[114:115] op_sel_hi:[1,0]
	s_nop 0
	v_mul_f32_e32 v110, 0xbfb8aa3b, v108
	v_mul_f32_e32 v111, 0xbfb8aa3b, v109
	v_exp_f32_e32 v110, v110
	v_exp_f32_e32 v111, v111
	v_add_f32_e32 v110, 1.0, v110
	v_add_f32_e32 v111, 1.0, v111
	v_rcp_f32_e32 v110, v110
	v_rcp_f32_e32 v111, v111
	s_nop 0
	v_pk_mul_f32 v[108:109], v[108:109], v[110:111]
	s_nop 0
	v_pk_mul_f32 v[102:103], v[102:103], v[108:109]
	v_mul_f32_e32 v108, 0xbfb8aa3b, v104
	v_mul_f32_e32 v109, 0xbfb8aa3b, v105
	v_exp_f32_e32 v108, v108
	v_exp_f32_e32 v109, v109
	v_add_f32_e32 v108, 1.0, v108
	v_add_f32_e32 v109, 1.0, v109
	v_rcp_f32_e32 v108, v108
	v_rcp_f32_e32 v109, v109
	s_nop 0
	v_pk_mul_f32 v[104:105], v[104:105], v[108:109]
	s_nop 0
	v_pk_mul_f32 v[104:105], v[96:97], v[104:105]
	v_pk_mul_f32 v[96:97], v[106:107], v[114:115] op_sel_hi:[1,0]
	s_nop 0
	v_mul_f32_e32 v106, 0xbfb8aa3b, v96
	v_mul_f32_e32 v107, 0xbfb8aa3b, v97
	v_exp_f32_e32 v106, v106
	v_exp_f32_e32 v107, v107
	v_add_f32_e32 v106, 1.0, v106
	v_add_f32_e32 v107, 1.0, v107
	v_rcp_f32_e32 v106, v106
	v_rcp_f32_e32 v107, v107
	s_nop 0
	v_pk_mul_f32 v[96:97], v[96:97], v[106:107]
	s_nop 0
	v_pk_mul_f32 v[106:107], v[98:99], v[96:97]
	v_cvt_pk_bf16_f32 v96, v100, v101
	v_mad_i64_i32 v[100:101], s[0:1], v112, s73, v[116:117]
	v_cvt_pk_bf16_f32 v97, v102, v103
	v_cvt_pk_bf16_f32 v98, v104, v105
	v_cvt_pk_bf16_f32 v99, v106, v107
	v_lshl_add_u64 v[100:101], v[100:101], 0, v[118:119]
	global_store_dwordx4 v[100:101], v[96:99], off
	s_nop 1
	v_or_b32_e32 v96, 32, v146
	s_waitcnt vmcnt(7)
; __device__ __forceinline__ unsigned pkbf(float lo, float hi) { f2_t v = {lo, hi}; return __builtin_bit_cast(unsigned, __builtin_convertvector(v, bf2_t)); }
; __device__ __forceinline__ float fsigmoid(float g) { return __builtin_amdgcn_rcpf(1.0f + __builtin_amdgcn_exp2f(-1.44269504f * g)); }
;     __device__ __forceinline__ void operator()(const f32x4 (&acc)[2][2][4][2], const Unit& u, int wr, int wc, int fr, int fq) const {
;     ...
;             for (int m = 0; m < 4; ++m) { const int row = row0 + ai * HALF + m * 16; const float sc = rsqrtf(ss[row] * invk + eps);
;                 float h[8];
; #pragma unroll
;                 for (int n = 0; n < 2; ++n)
; #pragma unroll
;                     for (int j = 0; j < 4; ++j) { const float g = acc[ai][0][m][n][j] * sc, up = acc[ai][1][m][n][j] * sc; h[4 * n + j] = g * fsigmoid(g) * up; }
;                 u32x4 w; w.x = pkbf(h[0], h[1]); w.y = pkbf(h[2], h[3]); w.z = pkbf(h[4], h[5]); w.w = pkbf(h[6], h[7]);
;                 *(u32x4*)(O + (size_t)row * ldc + col0) = w; }
	v_fmamk_f32 v97, v194, 0x3a800000, v134
	v_cmp_gt_f32_e32 vcc, s13, v97
	v_mul_f32_e32 v98, 0x4b800000, v97
	s_nop 0
	v_cndmask_b32_e32 v97, v97, v98, vcc
	v_rsq_f32_e32 v97, v97
	s_nop 0
	v_mul_f32_e32 v98, 0x45800000, v97
	v_cndmask_b32_e32 v98, v97, v98, vcc
	v_pk_mul_f32 v[92:93], v[92:93], v[98:99] op_sel_hi:[1,0]
	v_pk_mul_f32 v[84:85], v[84:85], v[98:99] op_sel_hi:[1,0]
	v_mul_f32_e32 v97, 0xbfb8aa3b, v92
	v_exp_f32_e32 v97, v97
	v_pk_mul_f32 v[86:87], v[86:87], v[98:99] op_sel_hi:[1,0]
	v_pk_mul_f32 v[88:89], v[88:89], v[98:99] op_sel_hi:[1,0]
	v_pk_mul_f32 v[80:81], v[80:81], v[98:99] op_sel_hi:[1,0]
	v_add_f32_e32 v97, 1.0, v97
	v_rcp_f32_e32 v100, v97
	v_mul_f32_e32 v97, 0xbfb8aa3b, v93
	v_exp_f32_e32 v97, v97
	v_pk_mul_f32 v[82:83], v[82:83], v[98:99] op_sel_hi:[1,0]
	v_add_f32_e32 v97, 1.0, v97
	v_rcp_f32_e32 v101, v97
	s_nop 0
	v_pk_mul_f32 v[92:93], v[92:93], v[100:101]
	s_nop 0
	v_pk_mul_f32 v[84:85], v[84:85], v[92:93]
	v_pk_mul_f32 v[92:93], v[94:95], v[98:99] op_sel_hi:[1,0]
	s_nop 0
	v_mul_f32_e32 v94, 0xbfb8aa3b, v92
	v_mul_f32_e32 v95, 0xbfb8aa3b, v93
	v_exp_f32_e32 v94, v94
	v_exp_f32_e32 v95, v95
	v_add_f32_e32 v94, 1.0, v94
	v_add_f32_e32 v95, 1.0, v95
	v_rcp_f32_e32 v94, v94
	v_rcp_f32_e32 v95, v95
	s_nop 0
	v_pk_mul_f32 v[92:93], v[92:93], v[94:95]
	s_nop 0
	v_pk_mul_f32 v[86:87], v[86:87], v[92:93]
	v_mul_f32_e32 v92, 0xbfb8aa3b, v88
	v_mul_f32_e32 v93, 0xbfb8aa3b, v89
	v_exp_f32_e32 v92, v92
	v_exp_f32_e32 v93, v93
	v_add_f32_e32 v92, 1.0, v92
	v_add_f32_e32 v93, 1.0, v93
	v_rcp_f32_e32 v92, v92
	v_rcp_f32_e32 v93, v93
	s_nop 0
	v_pk_mul_f32 v[88:89], v[88:89], v[92:93]
	s_nop 0
	v_pk_mul_f32 v[88:89], v[80:81], v[88:89]
	v_pk_mul_f32 v[80:81], v[90:91], v[98:99] op_sel_hi:[1,0]
	s_nop 0
	v_mul_f32_e32 v90, 0xbfb8aa3b, v80
	v_mul_f32_e32 v91, 0xbfb8aa3b, v81
	v_exp_f32_e32 v90, v90
	v_exp_f32_e32 v91, v91
	v_add_f32_e32 v90, 1.0, v90
	v_add_f32_e32 v91, 1.0, v91
	v_rcp_f32_e32 v90, v90
	v_rcp_f32_e32 v91, v91
	s_nop 0
	v_pk_mul_f32 v[80:81], v[80:81], v[90:91]
	s_nop 0
	v_pk_mul_f32 v[90:91], v[82:83], v[80:81]
	v_cvt_pk_bf16_f32 v80, v84, v85
	v_mad_i64_i32 v[84:85], s[0:1], v96, s73, v[116:117]
	v_cvt_pk_bf16_f32 v81, v86, v87
	v_cvt_pk_bf16_f32 v82, v88, v89
	v_cvt_pk_bf16_f32 v83, v90, v91
	v_lshl_add_u64 v[84:85], v[84:85], 0, v[118:119]
	global_store_dwordx4 v[84:85], v[80:83], off
	s_nop 1
	v_or_b32_e32 v80, 48, v146
	s_waitcnt vmcnt(7)
	v_fmamk_f32 v81, v195, 0x3a800000, v134
	v_cmp_gt_f32_e32 vcc, s13, v81
	v_mul_f32_e32 v82, 0x4b800000, v81
	s_nop 0
	v_cndmask_b32_e32 v81, v81, v82, vcc
	v_rsq_f32_e32 v81, v81
	s_nop 0
	v_mul_f32_e32 v82, 0x45800000, v81
	v_cndmask_b32_e32 v82, v81, v82, vcc
	v_pk_mul_f32 v[76:77], v[76:77], v[82:83] op_sel_hi:[1,0]
	v_pk_mul_f32 v[68:69], v[68:69], v[82:83] op_sel_hi:[1,0]
	v_mul_f32_e32 v81, 0xbfb8aa3b, v76
	v_exp_f32_e32 v81, v81
	v_pk_mul_f32 v[70:71], v[70:71], v[82:83] op_sel_hi:[1,0]
	v_pk_mul_f32 v[72:73], v[72:73], v[82:83] op_sel_hi:[1,0]
	v_pk_mul_f32 v[64:65], v[64:65], v[82:83] op_sel_hi:[1,0]
	v_add_f32_e32 v81, 1.0, v81
	v_rcp_f32_e32 v84, v81
	v_mul_f32_e32 v81, 0xbfb8aa3b, v77
	v_exp_f32_e32 v81, v81
	v_pk_mul_f32 v[66:67], v[66:67], v[82:83] op_sel_hi:[1,0]
	v_add_f32_e32 v81, 1.0, v81
	v_rcp_f32_e32 v85, v81
	s_nop 0
	v_pk_mul_f32 v[76:77], v[76:77], v[84:85]
	s_nop 0
	v_pk_mul_f32 v[68:69], v[68:69], v[76:77]
	v_pk_mul_f32 v[76:77], v[78:79], v[82:83] op_sel_hi:[1,0]
	s_nop 0
	v_mul_f32_e32 v78, 0xbfb8aa3b, v76
	v_mul_f32_e32 v79, 0xbfb8aa3b, v77
	v_exp_f32_e32 v78, v78
	v_exp_f32_e32 v79, v79
	v_add_f32_e32 v78, 1.0, v78
	v_add_f32_e32 v79, 1.0, v79
	v_rcp_f32_e32 v78, v78
	v_rcp_f32_e32 v79, v79
	s_nop 0
	v_pk_mul_f32 v[76:77], v[76:77], v[78:79]
	s_nop 0
	v_pk_mul_f32 v[70:71], v[70:71], v[76:77]
	v_mul_f32_e32 v76, 0xbfb8aa3b, v72
	v_mul_f32_e32 v77, 0xbfb8aa3b, v73
	v_exp_f32_e32 v76, v76
	v_exp_f32_e32 v77, v77
	v_add_f32_e32 v76, 1.0, v76
	v_add_f32_e32 v77, 1.0, v77
	v_rcp_f32_e32 v76, v76
	v_rcp_f32_e32 v77, v77
	s_nop 0
	v_pk_mul_f32 v[72:73], v[72:73], v[76:77]
	s_nop 0
	v_pk_mul_f32 v[72:73], v[64:65], v[72:73]
	v_pk_mul_f32 v[64:65], v[74:75], v[82:83] op_sel_hi:[1,0]
	s_nop 0
	v_mul_f32_e32 v74, 0xbfb8aa3b, v64
	v_mul_f32_e32 v75, 0xbfb8aa3b, v65
	v_exp_f32_e32 v74, v74
	v_exp_f32_e32 v75, v75
	v_add_f32_e32 v74, 1.0, v74
	v_add_f32_e32 v75, 1.0, v75
	v_rcp_f32_e32 v74, v74
	v_rcp_f32_e32 v75, v75
	s_nop 0
	v_pk_mul_f32 v[64:65], v[64:65], v[74:75]
	s_nop 0
	v_pk_mul_f32 v[74:75], v[66:67], v[64:65]
	v_cvt_pk_bf16_f32 v64, v68, v69
	v_mad_i64_i32 v[68:69], s[0:1], v80, s73, v[116:117]
	v_cvt_pk_bf16_f32 v65, v70, v71
	v_cvt_pk_bf16_f32 v66, v72, v73
	v_cvt_pk_bf16_f32 v67, v74, v75
	v_lshl_add_u64 v[68:69], v[68:69], 0, v[118:119]
	global_store_dwordx4 v[68:69], v[64:67], off
	s_nop 1
	v_add_u32_e32 v65, 0x80, v146
	s_waitcnt vmcnt(7)
; __device__ __forceinline__ unsigned pkbf(float lo, float hi) { f2_t v = {lo, hi}; return __builtin_bit_cast(unsigned, __builtin_convertvector(v, bf2_t)); }
; __device__ __forceinline__ float fsigmoid(float g) { return __builtin_amdgcn_rcpf(1.0f + __builtin_amdgcn_exp2f(-1.44269504f * g)); }
;     __device__ __forceinline__ void operator()(const f32x4 (&acc)[2][2][4][2], const Unit& u, int wr, int wc, int fr, int fq) const {
;     ...
;             for (int m = 0; m < 4; ++m) { const int row = row0 + ai * HALF + m * 16; const float sc = rsqrtf(ss[row] * invk + eps);
;                 float h[8];
; #pragma unroll
;                 for (int n = 0; n < 2; ++n)
; #pragma unroll
;                     for (int j = 0; j < 4; ++j) { const float g = acc[ai][0][m][n][j] * sc, up = acc[ai][1][m][n][j] * sc; h[4 * n + j] = g * fsigmoid(g) * up; }
;                 u32x4 w; w.x = pkbf(h[0], h[1]); w.y = pkbf(h[2], h[3]); w.z = pkbf(h[4], h[5]); w.w = pkbf(h[6], h[7]);
;                 *(u32x4*)(O + (size_t)row * ldc + col0) = w; }
	v_fmamk_f32 v64, v196, 0x3a800000, v134
	v_cmp_gt_f32_e32 vcc, s13, v64
	v_mul_f32_e32 v66, 0x4b800000, v64
	s_nop 0
	v_cndmask_b32_e32 v64, v64, v66, vcc
	v_rsq_f32_e32 v64, v64
	s_nop 0
	v_mul_f32_e32 v66, 0x45800000, v64
	v_cndmask_b32_e32 v64, v64, v66, vcc
	v_pk_mul_f32 v[60:61], v[60:61], v[64:65] op_sel_hi:[1,0]
	v_pk_mul_f32 v[52:53], v[52:53], v[64:65] op_sel_hi:[1,0]
	v_mul_f32_e32 v66, 0xbfb8aa3b, v60
	v_mul_f32_e32 v67, 0xbfb8aa3b, v61
	v_exp_f32_e32 v66, v66
	v_exp_f32_e32 v67, v67
	v_pk_mul_f32 v[54:55], v[54:55], v[64:65] op_sel_hi:[1,0]
	v_pk_mul_f32 v[56:57], v[56:57], v[64:65] op_sel_hi:[1,0]
	v_add_f32_e32 v66, 1.0, v66
	v_add_f32_e32 v67, 1.0, v67
	v_rcp_f32_e32 v66, v66
	v_rcp_f32_e32 v67, v67
	v_pk_mul_f32 v[48:49], v[48:49], v[64:65] op_sel_hi:[1,0]
	v_pk_mul_f32 v[50:51], v[50:51], v[64:65] op_sel_hi:[1,0]
	v_pk_mul_f32 v[60:61], v[60:61], v[66:67]
	s_nop 0
	v_pk_mul_f32 v[52:53], v[52:53], v[60:61]
	v_pk_mul_f32 v[60:61], v[62:63], v[64:65] op_sel_hi:[1,0]
	s_nop 0
	v_mul_f32_e32 v62, 0xbfb8aa3b, v60
	v_mul_f32_e32 v63, 0xbfb8aa3b, v61
	v_exp_f32_e32 v62, v62
	v_exp_f32_e32 v63, v63
	v_add_f32_e32 v62, 1.0, v62
	v_add_f32_e32 v63, 1.0, v63
	v_rcp_f32_e32 v62, v62
	v_rcp_f32_e32 v63, v63
	s_nop 0
	v_pk_mul_f32 v[60:61], v[60:61], v[62:63]
	s_nop 0
	v_pk_mul_f32 v[54:55], v[54:55], v[60:61]
	v_mul_f32_e32 v60, 0xbfb8aa3b, v56
	v_mul_f32_e32 v61, 0xbfb8aa3b, v57
	v_exp_f32_e32 v60, v60
	v_exp_f32_e32 v61, v61
	v_add_f32_e32 v60, 1.0, v60
	v_add_f32_e32 v61, 1.0, v61
	v_rcp_f32_e32 v60, v60
	v_rcp_f32_e32 v61, v61
	s_nop 0
	v_pk_mul_f32 v[56:57], v[56:57], v[60:61]
	s_nop 0
	v_pk_mul_f32 v[56:57], v[48:49], v[56:57]
	v_pk_mul_f32 v[48:49], v[58:59], v[64:65] op_sel_hi:[1,0]
	s_nop 0
	v_mul_f32_e32 v58, 0xbfb8aa3b, v48
	v_mul_f32_e32 v59, 0xbfb8aa3b, v49
	v_exp_f32_e32 v58, v58
	v_exp_f32_e32 v59, v59
	v_add_f32_e32 v58, 1.0, v58
	v_add_f32_e32 v59, 1.0, v59
	v_rcp_f32_e32 v58, v58
	v_rcp_f32_e32 v59, v59
	s_nop 0
	v_pk_mul_f32 v[48:49], v[48:49], v[58:59]
	s_nop 0
	v_pk_mul_f32 v[58:59], v[50:51], v[48:49]
	v_cvt_pk_bf16_f32 v48, v52, v53
	v_mad_i64_i32 v[52:53], s[0:1], v65, s73, v[116:117]
	v_cvt_pk_bf16_f32 v49, v54, v55
	v_cvt_pk_bf16_f32 v50, v56, v57
	v_cvt_pk_bf16_f32 v51, v58, v59
	v_lshl_add_u64 v[52:53], v[52:53], 0, v[118:119]
	global_store_dwordx4 v[52:53], v[48:51], off
	s_nop 1
	v_add_u32_e32 v49, 0x90, v146
	s_waitcnt vmcnt(7)
	v_fmamk_f32 v48, v197, 0x3a800000, v134
	v_cmp_gt_f32_e32 vcc, s13, v48
	v_mul_f32_e32 v50, 0x4b800000, v48
	s_nop 0
	v_cndmask_b32_e32 v48, v48, v50, vcc
	v_rsq_f32_e32 v48, v48
	s_nop 0
	v_mul_f32_e32 v50, 0x45800000, v48
	v_cndmask_b32_e32 v48, v48, v50, vcc
	v_pk_mul_f32 v[44:45], v[44:45], v[48:49] op_sel_hi:[1,0]
	v_pk_mul_f32 v[36:37], v[36:37], v[48:49] op_sel_hi:[1,0]
	v_mul_f32_e32 v50, 0xbfb8aa3b, v44
	v_mul_f32_e32 v51, 0xbfb8aa3b, v45
	v_exp_f32_e32 v50, v50
	v_exp_f32_e32 v51, v51
	v_pk_mul_f32 v[38:39], v[38:39], v[48:49] op_sel_hi:[1,0]
	v_pk_mul_f32 v[40:41], v[40:41], v[48:49] op_sel_hi:[1,0]
	v_add_f32_e32 v50, 1.0, v50
	v_add_f32_e32 v51, 1.0, v51
	v_rcp_f32_e32 v50, v50
	v_rcp_f32_e32 v51, v51
	v_pk_mul_f32 v[32:33], v[32:33], v[48:49] op_sel_hi:[1,0]
	v_pk_mul_f32 v[34:35], v[34:35], v[48:49] op_sel_hi:[1,0]
	v_pk_mul_f32 v[44:45], v[44:45], v[50:51]
	s_nop 0
	v_pk_mul_f32 v[36:37], v[36:37], v[44:45]
	v_pk_mul_f32 v[44:45], v[46:47], v[48:49] op_sel_hi:[1,0]
	s_nop 0
	v_mul_f32_e32 v46, 0xbfb8aa3b, v44
	v_mul_f32_e32 v47, 0xbfb8aa3b, v45
	v_exp_f32_e32 v46, v46
	v_exp_f32_e32 v47, v47
	v_add_f32_e32 v46, 1.0, v46
	v_add_f32_e32 v47, 1.0, v47
	v_rcp_f32_e32 v46, v46
	v_rcp_f32_e32 v47, v47
	s_nop 0
	v_pk_mul_f32 v[44:45], v[44:45], v[46:47]
	s_nop 0
	v_pk_mul_f32 v[38:39], v[38:39], v[44:45]
	v_mul_f32_e32 v44, 0xbfb8aa3b, v40
	v_mul_f32_e32 v45, 0xbfb8aa3b, v41
	v_exp_f32_e32 v44, v44
	v_exp_f32_e32 v45, v45
	v_add_f32_e32 v44, 1.0, v44
	v_add_f32_e32 v45, 1.0, v45
	v_rcp_f32_e32 v44, v44
	v_rcp_f32_e32 v45, v45
	s_nop 0
	v_pk_mul_f32 v[40:41], v[40:41], v[44:45]
	s_nop 0
	v_pk_mul_f32 v[40:41], v[32:33], v[40:41]
	v_pk_mul_f32 v[32:33], v[42:43], v[48:49] op_sel_hi:[1,0]
	s_nop 0
	v_mul_f32_e32 v42, 0xbfb8aa3b, v32
	v_mul_f32_e32 v43, 0xbfb8aa3b, v33
	v_exp_f32_e32 v42, v42
	v_exp_f32_e32 v43, v43
	v_add_f32_e32 v42, 1.0, v42
	v_add_f32_e32 v43, 1.0, v43
	v_rcp_f32_e32 v42, v42
	v_rcp_f32_e32 v43, v43
	s_nop 0
	v_pk_mul_f32 v[32:33], v[32:33], v[42:43]
	s_nop 0
	v_pk_mul_f32 v[42:43], v[34:35], v[32:33]
	v_cvt_pk_bf16_f32 v32, v36, v37
	v_mad_i64_i32 v[36:37], s[0:1], v49, s73, v[116:117]
	v_cvt_pk_bf16_f32 v33, v38, v39
	v_cvt_pk_bf16_f32 v34, v40, v41
	v_cvt_pk_bf16_f32 v35, v42, v43
	v_lshl_add_u64 v[36:37], v[36:37], 0, v[118:119]
	global_store_dwordx4 v[36:37], v[32:35], off
	s_nop 1
	v_add_u32_e32 v33, 0xa0, v146
	s_waitcnt vmcnt(7)
; __device__ __forceinline__ unsigned pkbf(float lo, float hi) { f2_t v = {lo, hi}; return __builtin_bit_cast(unsigned, __builtin_convertvector(v, bf2_t)); }
; __device__ __forceinline__ float fsigmoid(float g) { return __builtin_amdgcn_rcpf(1.0f + __builtin_amdgcn_exp2f(-1.44269504f * g)); }
; #define PG8_BAR __builtin_amdgcn_s_barrier()
;     __device__ __forceinline__ void operator()(const f32x4 (&acc)[2][2][4][2], const Unit& u, int wr, int wc, int fr, int fq) const {
;     ...
;             for (int m = 0; m < 4; ++m) { const int row = row0 + ai * HALF + m * 16; const float sc = rsqrtf(ss[row] * invk + eps);
;                 float h[8];
; #pragma unroll
;                 for (int n = 0; n < 2; ++n)
; #pragma unroll
;                     for (int j = 0; j < 4; ++j) { const float g = acc[ai][0][m][n][j] * sc, up = acc[ai][1][m][n][j] * sc; h[4 * n + j] = g * fsigmoid(g) * up; }
;                 u32x4 w; w.x = pkbf(h[0], h[1]); w.y = pkbf(h[2], h[3]); w.z = pkbf(h[4], h[5]); w.w = pkbf(h[6], h[7]);
;                 *(u32x4*)(O + (size_t)row * ldc + col0) = w; }
; template <class Epi, class Sched, bool ALIGN_EPI = false, bool SP2 = false>
; __device__ __forceinline__ void gemm_phase(PG8_LAS unsigned char* lds, const Gemm g, const Sched& S, const Epi& E) {
;     ...
;         if constexpr (ALIGN_EPI) { if (wr == 0) PG8_BAR; }
;         if constexpr (!Epi::AFTER_DRAIN) { E(acc, cur, wr, wc, fr, fq); S.done(cur); }
;         if (!has_next) break;
; #pragma unroll
;         for (int a = 0; a < 2; ++a)
; #pragma unroll
;             for (int b = 0; b < 2; ++b)
; #pragma unroll
;                 for (int m = 0; m < 4; ++m)
; #pragma unroll
;                     for (int n = 0; n < 2; ++n) acc[a][b][m][n] = (f32x4){0.f, 0.f, 0.f, 0.f};
;         cur = nxt; cA = nA; cB = nB; ++ui;
;         if constexpr (ALIGN_EPI) { if (wr == 1) PG8_BAR; }
	v_fmamk_f32 v32, v198, 0x3a800000, v134
	v_cmp_gt_f32_e32 vcc, s13, v32
	v_mul_f32_e32 v34, 0x4b800000, v32
	s_nop 0
	v_cndmask_b32_e32 v32, v32, v34, vcc
	v_rsq_f32_e32 v32, v32
	s_nop 0
	v_mul_f32_e32 v34, 0x45800000, v32
	v_cndmask_b32_e32 v32, v32, v34, vcc
	v_pk_mul_f32 v[28:29], v[28:29], v[32:33] op_sel_hi:[1,0]
	v_pk_mul_f32 v[20:21], v[20:21], v[32:33] op_sel_hi:[1,0]
	v_mul_f32_e32 v34, 0xbfb8aa3b, v28
	v_mul_f32_e32 v35, 0xbfb8aa3b, v29
	v_exp_f32_e32 v34, v34
	v_exp_f32_e32 v35, v35
	v_pk_mul_f32 v[22:23], v[22:23], v[32:33] op_sel_hi:[1,0]
	v_pk_mul_f32 v[24:25], v[24:25], v[32:33] op_sel_hi:[1,0]
	v_add_f32_e32 v34, 1.0, v34
	v_add_f32_e32 v35, 1.0, v35
	v_rcp_f32_e32 v34, v34
	v_rcp_f32_e32 v35, v35
	v_pk_mul_f32 v[16:17], v[16:17], v[32:33] op_sel_hi:[1,0]
	v_pk_mul_f32 v[18:19], v[18:19], v[32:33] op_sel_hi:[1,0]
	v_pk_mul_f32 v[28:29], v[28:29], v[34:35]
	s_nop 0
	v_pk_mul_f32 v[20:21], v[20:21], v[28:29]
	v_pk_mul_f32 v[28:29], v[30:31], v[32:33] op_sel_hi:[1,0]
	s_nop 0
	v_mul_f32_e32 v30, 0xbfb8aa3b, v28
	v_mul_f32_e32 v31, 0xbfb8aa3b, v29
	v_exp_f32_e32 v30, v30
	v_exp_f32_e32 v31, v31
	v_add_f32_e32 v30, 1.0, v30
	v_add_f32_e32 v31, 1.0, v31
	v_rcp_f32_e32 v30, v30
	v_rcp_f32_e32 v31, v31
	s_nop 0
	v_pk_mul_f32 v[28:29], v[28:29], v[30:31]
	s_nop 0
	v_pk_mul_f32 v[22:23], v[22:23], v[28:29]
	v_mul_f32_e32 v28, 0xbfb8aa3b, v24
	v_mul_f32_e32 v29, 0xbfb8aa3b, v25
	v_exp_f32_e32 v28, v28
	v_exp_f32_e32 v29, v29
	v_add_f32_e32 v28, 1.0, v28
	v_add_f32_e32 v29, 1.0, v29
	v_rcp_f32_e32 v28, v28
	v_rcp_f32_e32 v29, v29
	s_nop 0
	v_pk_mul_f32 v[24:25], v[24:25], v[28:29]
	s_nop 0
	v_pk_mul_f32 v[24:25], v[16:17], v[24:25]
	v_pk_mul_f32 v[16:17], v[26:27], v[32:33] op_sel_hi:[1,0]
	s_nop 0
	v_mul_f32_e32 v26, 0xbfb8aa3b, v16
	v_mul_f32_e32 v27, 0xbfb8aa3b, v17
	v_exp_f32_e32 v26, v26
	v_exp_f32_e32 v27, v27
	v_add_f32_e32 v26, 1.0, v26
	v_add_f32_e32 v27, 1.0, v27
	v_rcp_f32_e32 v26, v26
	v_rcp_f32_e32 v27, v27
	s_nop 0
	v_pk_mul_f32 v[16:17], v[16:17], v[26:27]
	s_nop 0
	v_pk_mul_f32 v[26:27], v[18:19], v[16:17]
	v_cvt_pk_bf16_f32 v16, v20, v21
	v_mad_i64_i32 v[20:21], s[0:1], v33, s73, v[116:117]
	v_cvt_pk_bf16_f32 v17, v22, v23
	v_cvt_pk_bf16_f32 v18, v24, v25
	v_cvt_pk_bf16_f32 v19, v26, v27
	v_lshl_add_u64 v[20:21], v[20:21], 0, v[118:119]
	global_store_dwordx4 v[20:21], v[16:19], off
	s_nop 1
	v_add_u32_e32 v17, 0xb0, v146
	s_waitcnt vmcnt(7)
	v_fmamk_f32 v16, v199, 0x3a800000, v134
	v_cmp_gt_f32_e32 vcc, s13, v16
	v_mul_f32_e32 v18, 0x4b800000, v16
	s_nop 0
	v_cndmask_b32_e32 v16, v16, v18, vcc
	v_rsq_f32_e32 v16, v16
	s_nop 0
	v_mul_f32_e32 v18, 0x45800000, v16
	v_cndmask_b32_e32 v16, v16, v18, vcc
	v_pk_mul_f32 v[12:13], v[12:13], v[16:17] op_sel_hi:[1,0]
	v_pk_mul_f32 v[4:5], v[4:5], v[16:17] op_sel_hi:[1,0]
	v_mul_f32_e32 v18, 0xbfb8aa3b, v12
	v_mul_f32_e32 v19, 0xbfb8aa3b, v13
	v_exp_f32_e32 v18, v18
	v_exp_f32_e32 v19, v19
	v_pk_mul_f32 v[6:7], v[6:7], v[16:17] op_sel_hi:[1,0]
	v_pk_mul_f32 v[8:9], v[8:9], v[16:17] op_sel_hi:[1,0]
	v_add_f32_e32 v18, 1.0, v18
	v_add_f32_e32 v19, 1.0, v19
	v_rcp_f32_e32 v18, v18
	v_rcp_f32_e32 v19, v19
	v_pk_mul_f32 v[0:1], v[0:1], v[16:17] op_sel_hi:[1,0]
	v_pk_mul_f32 v[2:3], v[2:3], v[16:17] op_sel_hi:[1,0]
	s_andn2_b64 vcc, exec, s[40:41]
	v_pk_mul_f32 v[12:13], v[12:13], v[18:19]
	s_nop 0
	v_pk_mul_f32 v[4:5], v[4:5], v[12:13]
	v_pk_mul_f32 v[12:13], v[14:15], v[16:17] op_sel_hi:[1,0]
	s_nop 0
	v_mul_f32_e32 v14, 0xbfb8aa3b, v12
	v_mul_f32_e32 v15, 0xbfb8aa3b, v13
	v_exp_f32_e32 v14, v14
	v_exp_f32_e32 v15, v15
	v_add_f32_e32 v14, 1.0, v14
	v_add_f32_e32 v15, 1.0, v15
	v_rcp_f32_e32 v14, v14
	v_rcp_f32_e32 v15, v15
	s_nop 0
	v_pk_mul_f32 v[12:13], v[12:13], v[14:15]
	s_nop 0
	v_pk_mul_f32 v[6:7], v[6:7], v[12:13]
	v_mul_f32_e32 v12, 0xbfb8aa3b, v8
	v_mul_f32_e32 v13, 0xbfb8aa3b, v9
	v_exp_f32_e32 v12, v12
	v_exp_f32_e32 v13, v13
	v_add_f32_e32 v12, 1.0, v12
	v_add_f32_e32 v13, 1.0, v13
	v_rcp_f32_e32 v12, v12
	v_rcp_f32_e32 v13, v13
	s_nop 0
	v_pk_mul_f32 v[8:9], v[8:9], v[12:13]
	s_nop 0
	v_pk_mul_f32 v[8:9], v[0:1], v[8:9]
	v_pk_mul_f32 v[0:1], v[10:11], v[16:17] op_sel_hi:[1,0]
	s_nop 0
	v_mul_f32_e32 v10, 0xbfb8aa3b, v0
	v_mul_f32_e32 v11, 0xbfb8aa3b, v1
	v_exp_f32_e32 v10, v10
	v_exp_f32_e32 v11, v11
	v_add_f32_e32 v10, 1.0, v10
	v_add_f32_e32 v11, 1.0, v11
	v_rcp_f32_e32 v10, v10
	v_rcp_f32_e32 v11, v11
	s_nop 0
	v_pk_mul_f32 v[0:1], v[0:1], v[10:11]
	s_nop 0
	v_pk_mul_f32 v[10:11], v[2:3], v[0:1]
	v_cvt_pk_bf16_f32 v0, v4, v5
	v_mad_i64_i32 v[4:5], s[0:1], v17, s73, v[116:117]
	v_cvt_pk_bf16_f32 v1, v6, v7
	v_cvt_pk_bf16_f32 v2, v8, v9
	v_cvt_pk_bf16_f32 v3, v10, v11
	v_lshl_add_u64 v[4:5], v[4:5], 0, v[118:119]
	global_store_dwordx4 v[4:5], v[0:3], off
	s_cbranch_vccnz .LBB0_40
	s_andn2_b64 vcc, exec, s[4:5]
	s_cbranch_vccnz .LBB0_39
	s_barrier
	s_branch .LBB0_39

; __device__ __forceinline__ void e1_pass(ArgP ap, int l, int gw, int NGW, int lane) {
;     ...
;     const float* wconv = ap->in[9] + (size_t)l * 3 * 512; const float* gkv = ap->in[12] + l * 256; float* out = ap->out;
;     const int c8 = 8 * lane;
;     ...
;     u32x4 w_gb, w_u2, w_u1, w_u0, n_gb, n_u2, n_u1, n_u0; u32x2 w_kv, n_kv; f32x4 w_p, n_p; bf16_t w_k1, w_k2, n_k1, n_k2; f2_t w_cs, n_cs;
;     E1_LOAD(w_, gw);
;     ...
;         for (int j = 0; j < 8; ++j) { const float cv = u0[j] * wconv[c8 + j] + u1[j] * wconv[512 + c8 + j] + u2[j] * wconv[1024 + c8 + j]; co[j] = gb[j] * cv; ss += co[j] * co[j]; }
;     ...
;             const f32x4 g = *(const f32x4*)(gkv + 4 * lane); f32x4 c = {v[0] * rs * g[0], v[1] * rs * g[1], v[2] * rs * g[2], v[3] * rs * g[3]};
.LBB0_470:
	v_lshlrev_b32_e32 v50, 2, v190
	v_lshlrev_b32_e32 v56, 3, v190
	v_mov_b32_e32 v57, v133
	v_and_b32_e32 v0, 7, v191
	v_lshl_add_u64 v[48:49], s[8:9], 0, v[56:57]
	s_andn2_b64 vcc, exec, s[2:3]
	v_lshlrev_b32_e32 v54, 2, v50
	v_lshlrev_b32_e32 v52, 1, v0
	s_cbranch_vccnz .LBB0_513
	s_cmp_lt_i32 s92, 0x10000
	s_cselect_b32 s0, 0x7ff, 31
	s_and_b32 s0, s0, s92
	s_lshl_b32 s1, s0, 4
	s_or_b32 s2, s1, 0x10000
	s_cmp_lt_i32 s92, 0x10000
	s_cselect_b32 s10, 40, 48
	s_cselect_b32 s29, 26, 18
	s_cselect_b32 s33, s1, s2
	s_ashr_i32 s93, s92, 31
	s_add_i32 s1, s92, 0xffff0000
	s_cmp_lt_i32 s92, 0x10000
	s_cselect_b32 s4, s92, s1
	s_cselect_b32 s5, s93, 0
	s_add_u32 s8, s54, 0x17c80000
	s_addc_u32 s9, s55, 0
	s_add_u32 s1, s54, 0x1bcc0000
	s_addc_u32 s12, s55, 0
	s_add_u32 s2, s54, 0x100000
	s_addc_u32 s3, s55, 0
	v_readlane_b32 s46, v255, 26
	v_readlane_b32 s47, v255, 27
	s_add_u32 s22, s46, s10
	s_mul_i32 s21, s92, 0x280
	s_addc_u32 s23, s47, 0
	s_mul_hi_i32 s20, s92, 0x280
	s_add_u32 s24, s1, s21
	s_addc_u32 s25, s12, s20
	s_lshl_b64 s[20:21], s[92:93], 9
	s_lshl_b64 s[40:41], s[92:93], 10
	s_add_u32 s42, s34, s40
	s_addc_u32 s43, s35, s41
	s_cmp_gt_u32 s0, 1
	s_cselect_b32 s44, 0xfffff800, 0
	s_cselect_b32 s10, -1, 0
	s_add_u32 s44, s42, s44
	s_addc_u32 s45, s43, s10
	s_cmp_eq_u32 s0, 0
	v_lshlrev_b32_e32 v132, 4, v190
	v_lshlrev_b32_e32 v59, 1, v50
	s_cselect_b32 s10, 0, 0xfffffc00
	global_load_dwordx2 v[84:85], v59, s[24:25]
	global_load_dwordx4 v[8:11], v132, s[44:45]
	s_cselect_b32 s0, 0, -1
	s_add_u32 s44, s42, s10
	s_addc_u32 s45, s43, s0
	v_lshl_add_u64 v[60:61], s[8:9], 0, v[132:133]
	s_add_u32 s8, s8, s40
	s_addc_u32 s9, s9, s41
	global_load_dwordx4 v[4:7], v132, s[44:45]
	global_load_dwordx4 v[40:43], v132, s[42:43]
	global_load_dwordx4 v[44:47], v132, s[8:9]
	s_load_dwordx2 s[8:9], s[46:47], 0x48
	s_load_dwordx2 s[40:41], s[46:47], 0x60
	s_lshl_b32 s42, s96, 8
	s_ashr_i32 s43, s42, 31
	s_load_dwordx2 s[22:23], s[22:23], 0x0
	s_lshl_b64 s[42:43], s[42:43], 2
	s_waitcnt lgkmcnt(0)
	s_add_u32 s40, s40, s42
	s_mul_i32 s10, s96, 0x1800
	s_addc_u32 s41, s41, s43
	s_mul_hi_i32 s0, s96, 0x1800
	s_add_u32 s42, s8, s10
	v_and_b32_e32 v58, 15, v191
	s_addc_u32 s43, s9, s0
	s_lshl_b64 s[8:9], s[96:97], s29
	s_add_u32 s0, s22, s8
	v_or_b32_e32 v2, s33, v58
	s_addc_u32 s8, s23, s9
	s_lshl_b64 s[4:5], s[4:5], 10
	v_lshlrev_b32_e32 v2, 3, v2
	s_add_u32 s4, s0, s4
	global_load_dwordx2 v[66:67], v2, s[2:3]
	v_lshlrev_b32_e32 v2, 1, v58
	s_addc_u32 s5, s8, s5
	global_load_ushort v107, v2, s[24:25] offset:544
	global_load_ushort v108, v2, s[24:25] offset:512
	global_load_dwordx4 v[16:19], v54, s[4:5]
	v_cmp_lt_i32_e32 vcc, v175, v174
	s_lshl_b64 s[4:5], s[96:97], 18
	s_lshl_b64 s[8:9], s[96:97], 26
	s_lshl_b32 s0, s96, 3
	v_cndmask_b32_e32 v2, v173, v175, vcc
	v_cmp_lt_i32_e32 vcc, v176, v174
	s_lshl_b32 s22, s96, 5
	v_lshlrev_b32_e32 v0, 5, v190
	v_mov_b32_e32 v1, v133
	v_lshlrev_b32_e32 v71, 2, v2
	v_cndmask_b32_e32 v2, v173, v176, vcc
	v_cmp_lt_i32_e32 vcc, v177, v174
	s_add_u32 s20, s38, s20
	v_lshlrev_b32_e32 v102, 2, v2
	v_cndmask_b32_e32 v2, v173, v177, vcc
	v_cmp_lt_i32_e32 vcc, v178, v174
	v_lshl_add_u64 v[74:75], s[42:43], 0, v[0:1]
	s_mov_b64 s[24:25], 0x1000
	s_addc_u32 s21, s39, s21
	s_ashr_i32 s29, s28, 31
	v_lshlrev_b32_e32 v103, 2, v2
	v_cndmask_b32_e32 v2, v173, v178, vcc
	v_cmp_lt_i32_e32 vcc, v179, v174
	v_lshl_add_u64 v[76:77], v[74:75], 0, s[24:25]
	v_lshl_add_u64 v[80:81], s[20:21], 0, v[56:57]
	s_lshl_b64 s[20:21], s[28:29], 9
	s_lshl_b64 s[24:25], s[92:93], 11
	v_lshlrev_b32_e32 v104, 2, v2
	v_cndmask_b32_e32 v2, v173, v179, vcc
	v_cmp_lt_i32_e32 vcc, v180, v174
	s_add_u32 s6, s6, s24
	v_mov_b32_e32 v55, v133
	v_lshlrev_b32_e32 v105, 2, v2
	v_cndmask_b32_e32 v2, v173, v180, vcc
	v_mov_b32_e32 v53, v133
	v_mov_b32_e32 v51, v133
	s_addc_u32 s7, s7, s25
	v_lshl_add_u64 v[62:63], s[52:53], 0, v[0:1]
	v_lshl_add_u64 v[64:65], s[52:53], 0, v[54:55]
	v_lshlrev_b32_e32 v106, 2, v2
	v_lshl_add_u64 v[68:69], s[40:41], 0, v[54:55]
	v_cmp_gt_u32_e64 s[40:41], 16, v190
	v_and_b32_e32 v70, 32, v50
	v_lshl_add_u64 v[72:73], s[48:49], 0, v[52:53]
	v_lshl_add_u64 v[78:79], s[52:53], 0, v[50:51]
	v_lshl_add_u64 v[82:83], s[6:7], 0, v[132:133]
	s_lshl_b64 s[6:7], s[28:29], 11
	v_lshlrev_b32_e32 v51, 1, v56
	v_lshlrev_b32_e32 v53, 1, v58
	s_mov_b32 s29, s92
	global_load_dwordx4 v[204:207], v[74:75], off offset:16
	global_load_dwordx4 v[200:203], v[74:75], off
	global_load_dwordx4 v[212:215], v[74:75], off offset:2064
	global_load_dwordx4 v[208:211], v[74:75], off offset:2048
	global_load_dwordx4 v[220:223], v[76:77], off offset:16
	global_load_dwordx4 v[216:219], v[76:77], off
	global_load_dwordx4 v[224:227], v[68:69], off
	s_waitcnt vmcnt(0)
	s_branch .LBB0_475

; __device__ __forceinline__ unsigned pkbf(float lo, float hi) { f2_t v = {lo, hi}; return __builtin_bit_cast(unsigned, __builtin_convertvector(v, bf2_t)); }
; __device__ __forceinline__ void e1_pass(ArgP ap, int l, int gw, int NGW, int lane) {
;     ...
;         { const f32x4 v = w_p;
;             u32x2 o; o.x = pkbf(v[0], v[1]); o.y = pkbf(v[2], v[3]); *(u32x2*)(pb + (size_t)r * 256 + 4 * lane) = o; }
;         w_gb = n_gb; w_u2 = n_u2; w_u1 = n_u1; w_u0 = n_u0; w_kv = n_kv; w_p = n_p; w_k1 = n_k1; w_k2 = n_k2; w_cs = n_cs;
.LBB0_474:
	s_or_b64 exec, exec, s[44:45]
	s_waitcnt vmcnt(7)
	v_cvt_pk_bf16_f32 v0, v16, v17
	v_cvt_pk_bf16_f32 v1, v18, v19
	v_mov_b64_e32 v[46:47], v[34:35]
	v_mov_b64_e32 v[42:43], v[22:23]
	v_mov_b64_e32 v[4:5], v[24:25]
	v_mov_b64_e32 v[8:9], v[28:29]
	v_mov_b64_e32 v[16:17], v[36:37]
	global_store_dwordx2 v[80:81], v[0:1], off
	v_lshl_add_u64 v[80:81], v[80:81], 0, s[20:21]
	v_lshl_add_u64 v[82:83], v[82:83], 0, s[6:7]
	s_cmp_gt_i32 s23, 0x100ff
	v_mov_b64_e32 v[44:45], v[32:33]
	v_mov_b64_e32 v[40:41], v[20:21]
	v_mov_b64_e32 v[6:7], v[26:27]
	v_mov_b64_e32 v[10:11], v[30:31]
	v_mov_b64_e32 v[84:85], v[86:87]
	v_mov_b64_e32 v[18:19], v[38:39]
	v_mov_b32_e32 v108, v55
	v_mov_b32_e32 v107, v57
	v_mov_b64_e32 v[66:67], v[88:89]
	s_mov_b32 s29, s23
	s_cbranch_scc1 .LBB0_513

; __device__ __forceinline__ void unpack8(const u32x4 w, float (&f)[8]) { f[0] = bflo(w.x); f[1] = bfhi(w.x); f[2] = bflo(w.y); f[3] = bfhi(w.y); f[4] = bflo(w.z); f[5] = bfhi(w.z); f[6] = bflo(w.w); f[7] = bfhi(w.w); }
; __device__ __forceinline__ void e1_pass(ArgP ap, int l, int gw, int NGW, int lane) {
;     ...
;     u32x4 w_gb, w_u2, w_u1, w_u0, n_gb, n_u2, n_u1, n_u0; u32x2 w_kv, n_kv; f32x4 w_p, n_p; bf16_t w_k1, w_k2, n_k1, n_k2; f2_t w_cs, n_cs;
;     E1_LOAD(w_, gw);
;     for (int r = gw; r < M; r += NGW) {
;         E1_LOAD(n_, r + NGW);
;         const bool isp = r < NP; const int b = isp ? (r >> 11) : ((r - NP) >> 5), t = isp ? (r & 2047) : ((r - NP) & 31), L = isp ? 2048 : 32;
;         const int kvrow = isp ? r : NP + b * 4128 + 4096 + t;
;         float gb[8], u0[8], u1[8], u2[8];
;         unpack8(w_gb, gb); unpack8(w_u2, u2); unpack8(w_u1, u1); unpack8(w_u0, u0);
;         if (t < 2) {
;             if (isp) {
; #pragma unroll
;                 for (int j = 0; j < 8; ++j) { u0[j] = 0.f; if (t < 1) u1[j] = 0.f; } }
;             else { const float* st0 = ap->in[4] + ((size_t)(l * 8 + b) * 2 + t) * 512 + c8; const float* st1 = ap->in[4] + ((size_t)(l * 8 + b) * 2 + 1) * 512 + c8;
; #pragma unroll
;                 for (int j = 0; j < 8; ++j) { u0[j] = st0[j]; if (t < 1) u1[j] = st1[j]; } } }
.LBB0_479:
	s_lshl_b64 s[24:25], s[56:57], 10
	s_add_u32 s24, s46, s24
	s_addc_u32 s25, s47, s25
	s_lshl_b32 s10, s33, 4
	s_or_b32 s33, s10, 0x10000
	global_load_dwordx4 v[36:39], v54, s[24:25]
	s_and_b64 s[24:25], s[38:39], exec
	s_cselect_b32 s10, s10, s33
	v_or_b32_e32 v0, s10, v58
	v_lshlrev_b32_e32 v0, 3, v0
	global_load_ushort v55, v53, s[42:43] offset:512
	global_load_ushort v57, v53, s[42:43] offset:544
	global_load_dwordx2 v[88:89], v0, s[2:3]
	s_cmp_gt_i32 s29, 0xffff
	s_cselect_b64 s[38:39], -1, 0
	s_add_i32 s10, s29, 0xffff0000
	s_lshr_b32 s51, s10, 5
	s_and_b32 s50, s29, 0x7ff
	s_and_b32 s33, s29, 31
	s_cmp_lt_i32 s29, 0x10000
	s_cselect_b64 s[44:45], -1, 0
	s_and_b64 s[24:25], s[44:45], exec
	s_cselect_b32 s10, s50, s33
	v_lshlrev_b32_e32 v0, 16, v4
	v_and_b32_e32 v1, 0xffff0000, v4
	v_lshlrev_b32_e32 v2, 16, v5
	v_and_b32_e32 v3, 0xffff0000, v5
	v_lshlrev_b32_e32 v4, 16, v6
	v_and_b32_e32 v5, 0xffff0000, v6
	v_lshlrev_b32_e32 v6, 16, v7
	s_cmp_gt_u32 s10, 1
	v_and_b32_e32 v7, 0xffff0000, v7
	s_cbranch_scc1 .LBB0_494
	s_mov_b64 s[42:43], -1
	s_and_b64 vcc, exec, s[38:39]
	s_cbranch_vccz .LBB0_491
	v_readlane_b32 s24, v255, 26
	v_readlane_b32 s25, v255, 27
	s_load_dwordx2 s[24:25], s[24:25], 0x20
	s_add_i32 s42, s51, s0
	s_ashr_i32 s43, s42, 31
	s_lshl_b64 s[46:47], s[42:43], 12
	s_lshl_b32 s42, s33, 11
	s_or_b32 s42, s46, s42
	s_waitcnt lgkmcnt(0)
	s_add_u32 s42, s24, s42
	s_addc_u32 s43, s25, s47
	v_lshlrev_b32_e32 v132, 2, v56
	global_load_dword v90, v132, s[42:43]
	s_add_u32 s24, s24, s46
	s_addc_u32 s25, s25, s47
	s_cmp_eq_u32 s33, 0
	v_mov_b64_e32 v[14:15], v[6:7]
	v_lshl_add_u64 v[96:97], s[24:25], 0, v[132:133]
	s_cselect_b64 s[46:47], -1, 0
	s_cmp_lg_u32 s33, 0
	v_mov_b64_e32 v[12:13], v[4:5]
	v_mov_b64_e32 v[10:11], v[2:3]
	v_mov_b64_e32 v[8:9], v[0:1]
	s_cbranch_scc1 .LBB0_483
	global_load_dword v91, v[96:97], off offset:2048
	v_mov_b64_e32 v[14:15], v[6:7]
	v_mov_b64_e32 v[8:9], v[0:1]
	v_mov_b64_e32 v[12:13], v[4:5]
	v_mov_b64_e32 v[10:11], v[2:3]
	s_waitcnt vmcnt(0)
	v_mov_b32_e32 v8, v91

; __device__ __forceinline__ unsigned pkbf(float lo, float hi) { f2_t v = {lo, hi}; return __builtin_bit_cast(unsigned, __builtin_convertvector(v, bf2_t)); }
; __device__ __forceinline__ float bflo(unsigned w) { return __uint_as_float(w << 16); }
; __device__ __forceinline__ float bfhi(unsigned w) { return __uint_as_float(w & 0xffff0000u); }
; __device__ __forceinline__ u32x4 pack8(const float (&f)[8]) { u32x4 w; w.x = pkbf(f[0], f[1]); w.y = pkbf(f[2], f[3]); w.z = pkbf(f[4], f[5]); w.w = pkbf(f[6], f[7]); return w; }
; __device__ __forceinline__ void e1_pass(ArgP ap, int l, int gw, int NGW, int lane) {
;     ...
;         float co[8]; float ss = 0.f;
; #pragma unroll
;         for (int j = 0; j < 8; ++j) { const float cv = u0[j] * wconv[c8 + j] + u1[j] * wconv[512 + c8 + j] + u2[j] * wconv[1024 + c8 + j]; co[j] = gb[j] * cv; ss += co[j] * co[j]; }
;         ss = wave_sum(ss); { const float rs = rsqrtf(ss * (1.0f / 512.0f) + EPS);
; #pragma unroll
;             for (int j = 0; j < 8; ++j) co[j] *= rs; }
;         *(u32x4*)(A3 + (size_t)r * 1024 + c8) = pack8(co);
;         if (t >= L - 2) { float* d = out + (isp ? O_CVP + ((size_t)(l * 32 + b) * 2 + (t - (L - 2))) * 512 : O_CVS + ((size_t)(l * 8 + b) * 2 + (t - (L - 2))) * 512) + c8;
;             *(f32x4*)d = (f32x4){u2[0], u2[1], u2[2], u2[3]}; *(f32x4*)(d + 4) = (f32x4){u2[4], u2[5], u2[6], u2[7]}; }
;         { const u32x2 w = w_kv; float v[4] = {bflo(w.x), bfhi(w.x), bflo(w.y), bfhi(w.y)};
;             float s2 = (v[0] * v[0] + v[1] * v[1]) + (v[2] * v[2] + v[3] * v[3]); s2 = wave_sum(s2); const float rs = rsqrtf(s2 * (1.0f / 256.0f) + EPS);
;             const f32x4 g = *(const f32x4*)(gkv + 4 * lane); f32x4 c = {v[0] * rs * g[0], v[1] * rs * g[1], v[2] * rs * g[2], v[3] * rs * g[3]};
;             float* d = out + (isp ? O_LATP + ((size_t)(l * 32 + b) * 2048 + t) * 256 : O_LATS + ((size_t)(l * 8 + b) * 32 + t) * 256) + 4 * lane; *(f32x4*)d = c;
;             u32x2 o; o.x = pkbf(c[0], c[1]); o.y = pkbf(c[2], c[3]); *(u32x2*)(Akv + (size_t)kvrow * 256 + 4 * lane) = o; }
.LBB0_495:
	s_waitcnt vmcnt(14)
	v_lshlrev_b32_e32 v12, 16, v40
	v_and_b32_e32 v13, 0xffff0000, v40
	v_lshlrev_b32_e32 v14, 16, v41
	v_and_b32_e32 v15, 0xffff0000, v41
	v_lshlrev_b32_e32 v8, 16, v42
	v_and_b32_e32 v9, 0xffff0000, v42
	v_lshlrev_b32_e32 v10, 16, v43
	v_and_b32_e32 v11, 0xffff0000, v43
	s_waitcnt vmcnt(17)
	v_lshlrev_b32_e32 v96, 16, v44
	v_and_b32_e32 v97, 0xffff0000, v44
	v_lshlrev_b32_e32 v44, 16, v45
	v_and_b32_e32 v45, 0xffff0000, v45
	v_lshlrev_b32_e32 v126, 16, v46
	v_and_b32_e32 v127, 0xffff0000, v46
	v_lshlrev_b32_e32 v46, 16, v47
	v_and_b32_e32 v47, 0xffff0000, v47
	s_ashr_i32 s56, s29, 11
	s_and_b64 s[24:25], s[44:45], exec
	s_cselect_b32 s42, 0x7fe, 30
	s_cmp_lt_u32 s10, s42
	v_pk_mul_f32 v[6:7], v[6:7], v[214:215]
	s_nop 0
	v_pk_fma_f32 v[6:7], v[98:99], v[206:207], v[6:7]
	v_pk_mul_f32 v[0:1], v[0:1], v[208:209]
	v_pk_mul_f32 v[2:3], v[2:3], v[210:211]
	v_pk_fma_f32 v[0:1], v[90:91], v[200:201], v[0:1]
	v_pk_fma_f32 v[2:3], v[92:93], v[202:203], v[2:3]
	v_pk_mul_f32 v[4:5], v[4:5], v[212:213]
	v_pk_fma_f32 v[6:7], v[222:223], v[10:11], v[6:7]
	v_pk_fma_f32 v[0:1], v[216:217], v[12:13], v[0:1]
	v_pk_fma_f32 v[2:3], v[218:219], v[14:15], v[2:3]
	v_pk_mul_f32 v[0:1], v[0:1], v[96:97]
	v_pk_fma_f32 v[4:5], v[94:95], v[204:205], v[4:5]
	v_pk_mul_f32 v[2:3], v[2:3], v[44:45]
	v_pk_mul_f32 v[40:41], v[0:1], v[0:1]
	v_pk_fma_f32 v[4:5], v[220:221], v[8:9], v[4:5]
	v_pk_mul_f32 v[42:43], v[2:3], v[2:3]
	v_add_f32_e32 v40, v40, v41
	v_pk_mul_f32 v[4:5], v[4:5], v[126:127]
	v_add_f32_e32 v40, v40, v42
	v_pk_mul_f32 v[94:95], v[4:5], v[4:5]
	v_add_f32_e32 v40, v40, v43
	v_pk_mul_f32 v[6:7], v[6:7], v[46:47]
	v_add_f32_e32 v40, v40, v94
	v_pk_mul_f32 v[46:47], v[6:7], v[6:7]
	v_add_f32_e32 v40, v40, v95
	v_add_f32_e32 v40, v40, v46
	v_add_f32_e32 v40, v40, v47
	ds_bpermute_b32 v41, v71, v40
	s_waitcnt lgkmcnt(0)
	v_add_f32_e32 v40, v40, v41
	ds_bpermute_b32 v41, v102, v40
	s_waitcnt lgkmcnt(0)
	v_add_f32_e32 v40, v40, v41
	ds_bpermute_b32 v41, v103, v40
	s_waitcnt lgkmcnt(0)
	v_add_f32_e32 v40, v40, v41
	ds_bpermute_b32 v41, v104, v40
	s_waitcnt lgkmcnt(0)
	v_add_f32_e32 v40, v40, v41
	ds_bpermute_b32 v41, v105, v40
	s_waitcnt lgkmcnt(0)
	v_add_f32_e32 v40, v40, v41
	ds_bpermute_b32 v41, v106, v40
	s_waitcnt lgkmcnt(0)
	v_add_f32_e32 v40, v40, v41
	v_fmamk_f32 v40, v40, 0x3b000000, v134
	v_cmp_gt_f32_e32 vcc, s13, v40
	v_mul_f32_e32 v41, 0x4b800000, v40
	s_nop 0
	v_cndmask_b32_e32 v40, v40, v41, vcc
	v_rsq_f32_e32 v40, v40
	s_nop 0
	v_mul_f32_e32 v41, 0x45800000, v40
	v_cndmask_b32_e32 v40, v40, v41, vcc
	v_pk_mul_f32 v[0:1], v[0:1], v[40:41] op_sel_hi:[1,0]
	v_pk_mul_f32 v[2:3], v[2:3], v[40:41] op_sel_hi:[1,0]
	v_pk_mul_f32 v[4:5], v[4:5], v[40:41] op_sel_hi:[1,0]
	v_pk_mul_f32 v[6:7], v[6:7], v[40:41] op_sel_hi:[1,0]
	v_cvt_pk_bf16_f32 v0, v0, v1
	v_cvt_pk_bf16_f32 v1, v2, v3
	v_cvt_pk_bf16_f32 v2, v4, v5
	v_cvt_pk_bf16_f32 v3, v6, v7
	global_store_dwordx4 v[82:83], v[0:3], off
	s_cbranch_scc1 .LBB0_497
	s_add_i32 s10, s51, s0
	s_sub_i32 s42, s33, 30
	s_add_i32 s43, s56, s22
	s_add_i32 s46, s50, 0xfffff802
	s_and_b64 s[24:25], s[44:45], exec
	s_cselect_b32 s24, s46, s42
	s_cselect_b32 s42, s43, s10
	s_mov_b32 s10, 0x19100000
	s_cselect_b32 s10, s10, 0x191d0000
	s_ashr_i32 s25, s24, 31
	s_lshl_b64 s[24:25], s[24:25], 11
	s_ashr_i32 s43, s42, 31
	v_lshl_add_u64 v[0:1], v[62:63], 0, s[24:25]
	v_lshl_add_u64 v[0:1], v[0:1], 0, s[10:11]
	s_lshl_b64 s[24:25], s[42:43], 12
	v_lshl_add_u64 v[0:1], v[0:1], 0, s[24:25]
	global_store_dwordx4 v[0:1], v[12:15], off
	global_store_dwordx4 v[0:1], v[8:11], off offset:16
.LBB0_497:
	s_nop 1
	v_and_b32_e32 v11, 0xffff0000, v84
	v_lshlrev_b32_e32 v4, 16, v85
	v_and_b32_e32 v9, 0xffff0000, v85
	v_mov_b32_e32 v8, v11
	v_lshlrev_b32_e32 v6, 16, v84
	v_mov_b32_e32 v7, v4
	v_pk_mul_f32 v[12:13], v[8:9], v[8:9]
	s_mov_b64 s[42:43], -1
	v_pk_fma_f32 v[12:13], v[6:7], v[6:7], v[12:13]
	s_and_b64 vcc, exec, s[38:39]
	v_add_f32_e32 v5, v12, v13
	ds_bpermute_b32 v7, v71, v5
	s_waitcnt lgkmcnt(0)
	v_add_f32_e32 v5, v5, v7
	ds_bpermute_b32 v7, v102, v5
	s_waitcnt lgkmcnt(0)
	v_add_f32_e32 v5, v5, v7
	ds_bpermute_b32 v7, v103, v5
	s_waitcnt lgkmcnt(0)
	v_add_f32_e32 v5, v5, v7
	ds_bpermute_b32 v7, v104, v5
	s_waitcnt lgkmcnt(0)
	v_add_f32_e32 v5, v5, v7
	ds_bpermute_b32 v7, v105, v5
	s_waitcnt lgkmcnt(0)
	v_add_f32_e32 v5, v5, v7
	ds_bpermute_b32 v7, v106, v5
	s_cbranch_vccz .LBB0_499
	s_add_i32 s24, s51, s0
	s_ashr_i32 s25, s24, 31
	s_lshl_b32 s10, s33, 8
	s_lshl_b64 s[46:47], s[24:25], 13
	s_or_b32 s10, s10, 0x6450000
	s_mov_b64 s[42:43], 0

; __device__ __forceinline__ unsigned pkbf(float lo, float hi) { f2_t v = {lo, hi}; return __builtin_bit_cast(unsigned, __builtin_convertvector(v, bf2_t)); }
; __device__ __forceinline__ void e1_pass(ArgP ap, int l, int gw, int NGW, int lane) {
;     ...
;             float s2 = (v[0] * v[0] + v[1] * v[1]) + (v[2] * v[2] + v[3] * v[3]); s2 = wave_sum(s2); const float rs = rsqrtf(s2 * (1.0f / 256.0f) + EPS);
;             const f32x4 g = *(const f32x4*)(gkv + 4 * lane); f32x4 c = {v[0] * rs * g[0], v[1] * rs * g[1], v[2] * rs * g[2], v[3] * rs * g[3]};
;             float* d = out + (isp ? O_LATP + ((size_t)(l * 32 + b) * 2048 + t) * 256 : O_LATS + ((size_t)(l * 8 + b) * 32 + t) * 256) + 4 * lane; *(f32x4*)d = c;
;             u32x2 o; o.x = pkbf(c[0], c[1]); o.y = pkbf(c[2], c[3]); *(u32x2*)(Akv + (size_t)kvrow * 256 + 4 * lane) = o; }
.LBB0_501:
	s_waitcnt lgkmcnt(0)
	v_add_f32_e32 v5, v5, v7
	v_fmamk_f32 v5, v5, 0x3b800000, v134
	v_mul_f32_e32 v7, 0x4b800000, v5
	v_cmp_gt_f32_e32 vcc, s13, v5
	s_and_b64 s[24:25], s[44:45], exec
	s_cselect_b32 s24, s56, s51
	v_cndmask_b32_e32 v5, v5, v7, vcc
	v_rsq_f32_e32 v8, v5
	s_mulk_i32 s24, 0x1020
	s_or_b32 s24, s24, s33
	v_mov_b32_e32 v5, v9
	v_mul_f32_e32 v9, 0x45800000, v8
	s_add_i32 s42, s24, 0x11000
	v_cndmask_b32_e32 v8, v8, v9, vcc
	s_and_b64 s[24:25], s[44:45], exec
	v_mov_b32_e32 v7, v11
	v_pk_mul_f32 v[4:5], v[8:9], v[4:5] op_sel_hi:[0,1]
	s_cselect_b32 s42, s29, s42
	v_pk_mul_f32 v[6:7], v[8:9], v[6:7] op_sel_hi:[0,1]
	v_pk_mul_f32 v[2:3], v[226:227], v[4:5]
	v_lshl_add_u64 v[4:5], s[46:47], 2, v[64:65]
	s_ashr_i32 s43, s42, 31
	v_pk_mul_f32 v[0:1], v[224:225], v[6:7]
	v_lshl_add_u64 v[4:5], s[10:11], 2, v[4:5]
	s_lshl_b64 s[24:25], s[42:43], 9
	global_store_dwordx4 v[4:5], v[0:3], off
	s_nop 1
	v_cvt_pk_bf16_f32 v0, v0, v1
	v_cvt_pk_bf16_f32 v1, v2, v3
	v_lshl_add_u64 v[2:3], v[48:49], 0, s[24:25]
	global_store_dwordx2 v[2:3], v[0:1], off
	s_and_saveexec_b64 s[44:45], s[40:41]
	s_cbranch_execz .LBB0_474
	s_mov_b64 s[46:47], -1
	s_and_b64 vcc, exec, s[38:39]
	s_cbranch_vccz .LBB0_504
	s_add_i32 s38, s51, s0
	s_mov_b64 s[46:47], 0
